# GQA attention loop: softmax row-sum via v_pk_add_f32 pairs (f32 accumulate)
# baseline (speedup 1.0000x reference)
.LBB0_522:
	s_cmp_lt_u32 s15, s10
	s_cselect_b32 s4, 0, s10
	s_cselect_b32 s5, s40, s7
	s_lshl_b32 s4, s4, 5
	s_sub_i32 s4, s5, s4
	s_add_i32 s30, s21, s4
	s_add_i32 s4, s11, s15
	v_add_u32_e32 v66, s30, v189
	s_cmp_lt_u32 s4, s10
	v_ashrrev_i32_e32 v67, 31, v66
	s_cselect_b32 s4, 0, s10
	v_lshlrev_b64 v[66:67], 10, v[66:67]
	s_cselect_b32 s5, s40, s7
	s_lshl_b32 s4, s4, 5
	v_add_u32_e32 v228, 0xec00, v193
	v_add_u32_e32 v229, 0x4800, v192
	v_add_u32_e32 v230, 0x6c00, v192
	v_lshl_add_u64 v[66:67], v[178:179], 0, v[66:67]
	s_sub_i32 s4, s5, s4
	s_add_i32 s5, s33, s21
	s_waitcnt vmcnt(9)
	ds_write_b128 v191, v[130:133]
	s_waitcnt vmcnt(8)
	ds_write2_b64 v192, v[134:135], v[136:137] offset1:1
	s_waitcnt vmcnt(7)
	ds_write_b128 v191, v[142:145] offset:12800
	s_waitcnt vmcnt(6)
	ds_write2_b64 v228, v[138:139], v[140:141] offset1:1
	s_waitcnt vmcnt(5)
	ds_write_b128 v191, v[150:153] offset:25600
	s_waitcnt vmcnt(4)
	ds_write2_b64 v229, v[146:147], v[148:149] offset1:1
	s_waitcnt vmcnt(3)
	ds_write_b128 v191, v[158:161] offset:38400
	s_waitcnt vmcnt(2)
	ds_write2_b64 v230, v[154:155], v[156:157] offset1:1
	s_waitcnt vmcnt(1)
	ds_write_b128 v194, v[162:165] offset:256
	s_waitcnt vmcnt(0)
	ds_write_b128 v195, v[166:169] offset:256
	s_waitcnt lgkmcnt(0)
	s_barrier
	global_load_dwordx4 v[130:133], v[66:67], off
	v_lshl_add_u64 v[66:67], s[30:31], 1, v[180:181]
	s_add_i32 s30, s5, s4
	s_add_i32 s4, s4, s21
	global_load_dwordx4 v[134:137], v[66:67], off
	v_add_u32_e32 v66, s4, v201
	s_add_i32 s4, s18, s15
	s_cmp_lt_u32 s4, s10
	v_ashrrev_i32_e32 v67, 31, v66
	s_cselect_b32 s4, 0, s10
	v_lshlrev_b64 v[66:67], 10, v[66:67]
	s_cselect_b32 s5, s40, s7
	s_lshl_b32 s4, s4, 5
	v_lshl_add_u64 v[66:67], v[178:179], 0, v[66:67]
	s_sub_i32 s4, s5, s4
	s_add_i32 s5, s39, s21
	global_load_dwordx4 v[142:145], v[66:67], off
	v_lshl_add_u64 v[66:67], s[30:31], 1, v[180:181]
	s_add_i32 s30, s5, s4
	s_add_i32 s4, s4, s21
	global_load_dwordx4 v[138:141], v[66:67], off
	v_add_u32_e32 v66, s4, v199
	s_add_i32 s4, s19, s15
	s_cmp_lt_u32 s4, s10
	v_ashrrev_i32_e32 v67, 31, v66
	s_cselect_b32 s4, 0, s10
	v_lshlrev_b64 v[66:67], 10, v[66:67]
	s_cselect_b32 s5, s40, s7
	s_lshl_b32 s4, s4, 5
	v_lshl_add_u64 v[66:67], v[178:179], 0, v[66:67]
	s_sub_i32 s4, s5, s4
	s_add_i32 s5, s20, s21
	global_load_dwordx4 v[150:153], v[66:67], off
	v_lshl_add_u64 v[66:67], s[30:31], 1, v[180:181]
	s_add_i32 s30, s5, s4
	s_add_i32 s4, s4, s21
	global_load_dwordx4 v[146:149], v[66:67], off
	v_add_u32_e32 v66, s4, v200
	v_ashrrev_i32_e32 v67, 31, v66
	v_lshlrev_b64 v[66:67], 10, v[66:67]
	v_lshl_add_u64 v[66:67], v[178:179], 0, v[66:67]
	global_load_dwordx4 v[158:161], v[66:67], off
	v_lshl_add_u64 v[66:67], s[30:31], 1, v[180:181]
	v_cmp_gt_i32_e32 vcc, s10, v197
	v_mov_b32_e32 v68, s10
	global_load_dwordx4 v[154:157], v[66:67], off
	v_cndmask_b32_e64 v66, v68, 0, vcc
	v_mov_b32_e32 v69, s7
	v_mov_b32_e32 v70, s40
	v_cndmask_b32_e32 v67, v69, v70, vcc
	v_lshlrev_b32_e32 v66, 5, v66
	v_sub_u32_e32 v66, v67, v66
	v_add3_u32 v66, v198, s21, v66
	v_ashrrev_i32_e32 v67, 31, v66
	v_lshlrev_b64 v[66:67], 7, v[66:67]
	v_lshl_add_u64 v[66:67], v[182:183], 0, v[66:67]
	global_load_dwordx4 v[162:165], v[66:67], off
	v_add_u32_e32 v66, s18, v197
	v_cmp_gt_i32_e32 vcc, s10, v66
	v_mov_b32_e32 v0, v185
	v_mov_b32_e32 v235, v184
	v_cndmask_b32_e64 v66, v68, 0, vcc
	v_cndmask_b32_e32 v67, v69, v70, vcc
	v_lshlrev_b32_e32 v66, 5, v66
	v_sub_u32_e32 v66, v67, v66
	v_add3_u32 v66, v196, s21, v66
	v_ashrrev_i32_e32 v67, 31, v66
	v_lshlrev_b64 v[66:67], 7, v[66:67]
	v_lshl_add_u64 v[66:67], v[182:183], 0, v[66:67]
	global_load_dwordx4 v[166:169], v[66:67], off
	ds_read_b128 v[66:69], v190
	ds_read_b128 v[236:239], v190 offset:32
	s_waitcnt lgkmcnt(1)
	v_mfma_f32_32x32x16_bf16 v[66:81], v[66:69], v[118:121], 0
	v_add_u32_e32 v234, 0xc800, v227
	v_add_u32_e32 v231, 0xd800, v227
	s_add_i32 s21, s21, 32
	s_add_i32 s15, s15, 1
	v_add_u32_e32 v197, 1, v197
	s_cmp_lg_u32 s33, s21
	s_waitcnt lgkmcnt(0)
	v_mfma_f32_32x32x16_bf16 v[66:81], v[236:239], v[110:113], v[66:81]
	ds_read_b128 v[236:239], v190 offset:64
	s_waitcnt lgkmcnt(0)
	v_mfma_f32_32x32x16_bf16 v[66:81], v[236:239], v[106:109], v[66:81]
	ds_read_b128 v[236:239], v190 offset:96
	s_waitcnt lgkmcnt(0)
	v_mfma_f32_32x32x16_bf16 v[66:81], v[236:239], v[102:105], v[66:81]
	ds_read_b128 v[236:239], v190 offset:128
	s_waitcnt lgkmcnt(0)
	v_mfma_f32_32x32x16_bf16 v[66:81], v[236:239], v[98:101], v[66:81]
	ds_read_b128 v[236:239], v190 offset:160
	s_waitcnt lgkmcnt(0)
	v_mfma_f32_32x32x16_bf16 v[66:81], v[236:239], v[94:97], v[66:81]
	ds_read_b128 v[236:239], v190 offset:192
	s_waitcnt lgkmcnt(0)
	v_mfma_f32_32x32x16_bf16 v[66:81], v[236:239], v[90:93], v[66:81]
	ds_read_b128 v[236:239], v190 offset:224
	s_waitcnt lgkmcnt(0)
	v_mfma_f32_32x32x16_bf16 v[66:81], v[236:239], v[86:89], v[66:81]
	ds_read_b128 v[236:239], v190 offset:256
	s_waitcnt lgkmcnt(0)
	v_mfma_f32_32x32x16_bf16 v[66:81], v[236:239], v[122:125], v[66:81]
	ds_read_b128 v[236:239], v190 offset:288
	s_waitcnt lgkmcnt(0)
	v_mfma_f32_32x32x16_bf16 v[66:81], v[236:239], v[114:117], v[66:81]
	ds_read_b128 v[236:239], v190 offset:320
	s_waitcnt lgkmcnt(0)
	v_mfma_f32_32x32x16_bf16 v[66:81], v[236:239], v[126:129], v[66:81]
	ds_read_b128 v[236:239], v190 offset:352
	s_waitcnt lgkmcnt(0)
	v_mfma_f32_32x32x16_bf16 v[66:81], v[236:239], v[82:85], v[66:81]
	s_nop 11
	v_max_f32_e32 v184, v67, v67
	v_max_f32_e32 v185, v66, v66
	v_max_f32_e32 v184, v185, v184
	v_max3_f32 v184, v184, v68, v69
	v_max3_f32 v184, v184, v70, v71
	v_max3_f32 v184, v184, v72, v73
	v_max3_f32 v184, v184, v74, v75
	v_max3_f32 v184, v184, v76, v77
	v_max3_f32 v184, v184, v78, v79
	v_max3_f32 v184, v184, v80, v81
	v_mov_b32_e32 v185, v184
	s_nop 1
	v_permlane32_swap_b32 v185, v184
	s_waitcnt lgkmcnt(0)
	v_max3_f32 v185, v0, v184, v185
	v_mov_b32_e32 v184, v81
	v_pk_mul_f32 v[232:233], v[184:185], s[26:27] op_sel_hi:[1,0]
	v_sub_f32_e32 v0, v0, v185
	v_pk_fma_f32 v[66:67], v[66:67], s[26:27], v[232:233] op_sel:[0,0,1] op_sel_hi:[1,0,1] neg_lo:[0,0,1] neg_hi:[0,0,1]
	v_exp_f32_e32 v66, v66
	v_exp_f32_e32 v67, v67
	v_pk_fma_f32 v[68:69], v[68:69], s[26:27], v[232:233] op_sel:[0,0,1] op_sel_hi:[1,0,1] neg_lo:[0,0,1] neg_hi:[0,0,1]
	v_exp_f32_e32 v68, v68
	v_exp_f32_e32 v69, v69
	v_pk_fma_f32 v[70:71], v[70:71], s[26:27], v[232:233] op_sel:[0,0,1] op_sel_hi:[1,0,1] neg_lo:[0,0,1] neg_hi:[0,0,1]
	v_exp_f32_e32 v70, v70
	v_exp_f32_e32 v71, v71
	v_pk_fma_f32 v[72:73], v[72:73], s[26:27], v[232:233] op_sel:[0,0,1] op_sel_hi:[1,0,1] neg_lo:[0,0,1] neg_hi:[0,0,1]
	v_exp_f32_e32 v72, v72
	v_exp_f32_e32 v73, v73
	v_pk_fma_f32 v[74:75], v[74:75], s[26:27], v[232:233] op_sel:[0,0,1] op_sel_hi:[1,0,1] neg_lo:[0,0,1] neg_hi:[0,0,1]
	v_exp_f32_e32 v74, v74
	v_exp_f32_e32 v75, v75
	v_pk_fma_f32 v[76:77], v[76:77], s[26:27], v[232:233] op_sel:[0,0,1] op_sel_hi:[1,0,1] neg_lo:[0,0,1] neg_hi:[0,0,1]
	v_exp_f32_e32 v76, v76
	v_exp_f32_e32 v77, v77
	v_pk_fma_f32 v[78:79], v[78:79], s[26:27], v[232:233] op_sel:[0,0,1] op_sel_hi:[1,0,1] neg_lo:[0,0,1] neg_hi:[0,0,1]
	v_exp_f32_e32 v78, v78
	v_exp_f32_e32 v79, v79
	v_fma_f32 v80, v80, s26, -v233
	v_exp_f32_e32 v80, v80
	v_sub_f32_e32 v81, v232, v233
	v_exp_f32_e32 v81, v81
	v_mul_f32_e32 v0, 0x3dd53b94, v0
	v_exp_f32_e32 v0, v0
	v_pk_add_f32 v[232:233], v[66:67], v[68:69]
	v_pk_add_f32 v[232:233], v[232:233], v[70:71]
	v_pk_add_f32 v[232:233], v[232:233], v[72:73]
	v_pk_add_f32 v[232:233], v[232:233], v[74:75]
	v_pk_add_f32 v[232:233], v[232:233], v[76:77]
	v_pk_add_f32 v[232:233], v[232:233], v[78:79]
	v_pk_add_f32 v[232:233], v[232:233], v[80:81]
	v_add_f32_e32 v184, v232, v233
	v_cvt_pk_bf16_f32 v66, v66, v67
	v_cvt_pk_bf16_f32 v67, v68, v69
	v_cvt_pk_bf16_f32 v68, v70, v71
	v_cvt_pk_bf16_f32 v69, v72, v73
	v_cvt_pk_bf16_f32 v70, v74, v75
	v_cvt_pk_bf16_f32 v71, v76, v77
	v_cvt_pk_bf16_f32 v72, v78, v79
	v_cvt_pk_bf16_f32 v73, v80, v81
	ds_read2_b64 v[74:77], v234 offset1:2
	ds_read2_b64 v[78:81], v234 offset0:4 offset1:6
	v_pk_mul_f32 v[16:17], v[16:17], v[0:1] op_sel_hi:[1,0]
	v_pk_mul_f32 v[14:15], v[14:15], v[0:1] op_sel_hi:[1,0]
	v_pk_mul_f32 v[12:13], v[12:13], v[0:1] op_sel_hi:[1,0]
	v_pk_mul_f32 v[10:11], v[10:11], v[0:1] op_sel_hi:[1,0]
	v_pk_mul_f32 v[8:9], v[8:9], v[0:1] op_sel_hi:[1,0]
	v_pk_mul_f32 v[6:7], v[6:7], v[0:1] op_sel_hi:[1,0]
	v_pk_mul_f32 v[4:5], v[4:5], v[0:1] op_sel_hi:[1,0]
	v_pk_mul_f32 v[2:3], v[2:3], v[0:1] op_sel_hi:[1,0]
	v_add_u32_e32 v233, 0xd000, v227
	v_pk_mul_f32 v[48:49], v[48:49], v[0:1] op_sel_hi:[1,0]
	s_waitcnt lgkmcnt(1)
	v_mfma_f32_32x32x16_bf16 v[2:17], v[74:77], v[66:69], v[2:17]
	ds_read2_b64 v[74:77], v233 offset0:32 offset1:34
	v_mul_f32_e64 v46, v46, v0
	v_mul_f32_e64 v47, v47, v0
	v_mul_f32_e64 v44, v44, v0
	v_mul_f32_e64 v45, v45, v0
	v_pk_mul_f32 v[42:43], v[42:43], v[0:1] op_sel_hi:[1,0]
	v_pk_mul_f32 v[40:41], v[40:41], v[0:1] op_sel_hi:[1,0]
	v_pk_mul_f32 v[38:39], v[38:39], v[0:1] op_sel_hi:[1,0]
	v_pk_mul_f32 v[36:37], v[36:37], v[0:1] op_sel_hi:[1,0]
	v_pk_mul_f32 v[34:35], v[34:35], v[0:1] op_sel_hi:[1,0]
	v_pk_mul_f32 v[64:65], v[64:65], v[0:1] op_sel_hi:[1,0]
	v_pk_mul_f32 v[62:63], v[62:63], v[0:1] op_sel_hi:[1,0]
	s_waitcnt lgkmcnt(0)
	v_mfma_f32_32x32x16_bf16 v[34:49], v[74:77], v[66:69], v[34:49]
	ds_read2_b64 v[74:77], v233 offset0:36 offset1:38
	v_mul_f32_e64 v60, v60, v0
	v_mul_f32_e64 v61, v61, v0
	v_mul_f32_e64 v58, v58, v0
	v_mul_f32_e64 v59, v59, v0
	v_pk_mul_f32 v[56:57], v[56:57], v[0:1] op_sel_hi:[1,0]
	v_pk_mul_f32 v[54:55], v[54:55], v[0:1] op_sel_hi:[1,0]
	v_pk_mul_f32 v[52:53], v[52:53], v[0:1] op_sel_hi:[1,0]
	v_pk_mul_f32 v[50:51], v[50:51], v[0:1] op_sel_hi:[1,0]
	s_waitcnt lgkmcnt(0)
	v_mfma_f32_32x32x16_bf16 v[34:49], v[74:77], v[70:73], v[34:49]
	ds_read2_b64 v[74:77], v231 offset0:64 offset1:66
	v_add_u32_e32 v232, 0xe000, v227
	v_mul_f32_e64 v32, v32, v0
	v_mul_f32_e64 v33, v33, v0
	v_mul_f32_e64 v30, v30, v0
	v_mul_f32_e64 v31, v31, v0
	v_pk_mul_f32 v[28:29], v[28:29], v[0:1] op_sel_hi:[1,0]
	v_pk_mul_f32 v[26:27], v[26:27], v[0:1] op_sel_hi:[1,0]
	v_pk_mul_f32 v[24:25], v[24:25], v[0:1] op_sel_hi:[1,0]
	s_waitcnt lgkmcnt(0)
	v_mfma_f32_32x32x16_bf16 v[50:65], v[74:77], v[66:69], v[50:65]
	ds_read2_b64 v[74:77], v231 offset0:68 offset1:70
	v_mul_f32_e64 v22, v22, v0
	v_mul_f32_e64 v23, v23, v0
	v_mul_f32_e64 v20, v20, v0
	v_mul_f32_e64 v21, v21, v0
	v_pk_mul_f32 v[18:19], v[18:19], v[0:1] op_sel_hi:[1,0]
	v_fmac_f32_e32 v184, v235, v0
	s_waitcnt lgkmcnt(0)
	v_mfma_f32_32x32x16_bf16 v[50:65], v[74:77], v[70:73], v[50:65]
	ds_read2_b64 v[74:77], v232 offset0:96 offset1:98
	s_waitcnt lgkmcnt(0)
	v_mfma_f32_32x32x16_bf16 v[18:33], v[74:77], v[66:69], v[18:33]
	ds_read2_b64 v[66:69], v232 offset0:100 offset1:102
	s_waitcnt lgkmcnt(0)
	s_barrier
	v_mfma_f32_32x32x16_bf16 v[2:17], v[78:81], v[70:73], v[2:17]
	v_mfma_f32_32x32x16_bf16 v[18:33], v[66:69], v[70:73], v[18:33]
	s_cbranch_scc1 .LBB0_522
	s_waitcnt vmcnt(9)
	ds_write_b128 v191, v[130:133]
	s_waitcnt vmcnt(8)
	ds_write2_b64 v192, v[134:135], v[136:137] offset1:1
	s_waitcnt vmcnt(7)
	ds_write_b128 v191, v[142:145] offset:12800
	s_waitcnt vmcnt(6)
	ds_write2_b64 v228, v[138:139], v[140:141] offset1:1
	s_waitcnt vmcnt(5)
	ds_write_b128 v191, v[150:153] offset:25600
	s_waitcnt vmcnt(4)
	ds_write2_b64 v229, v[146:147], v[148:149] offset1:1
	s_waitcnt vmcnt(3)
	ds_write_b128 v191, v[158:161] offset:38400
	s_waitcnt vmcnt(2)
	ds_write2_b64 v230, v[154:155], v[156:157] offset1:1
	s_waitcnt vmcnt(1)
	ds_write_b128 v194, v[162:165] offset:256
	s_waitcnt vmcnt(0)
	ds_write_b128 v195, v[166:169] offset:256
	s_waitcnt lgkmcnt(0)
	s_barrier
	ds_read_b128 v[66:69], v190
	ds_read_b128 v[130:133], v190 offset:32
	s_waitcnt lgkmcnt(1)
	v_mfma_f32_32x32x16_bf16 v[66:81], v[66:69], v[118:121], 0
	v_readlane_b32 s4, v253, 17
	s_mov_b32 s7, 0xf149f2ca
	s_mov_b32 s39, s31
	s_waitcnt lgkmcnt(0)
	v_mfma_f32_32x32x16_bf16 v[66:81], v[130:133], v[110:113], v[66:81]
	ds_read_b128 v[110:113], v190 offset:64
	ds_read_b128 v[118:121], v190 offset:96
	s_waitcnt lgkmcnt(1)
	v_mfma_f32_32x32x16_bf16 v[66:81], v[110:113], v[106:109], v[66:81]
	v_ashrrev_i32_e32 v110, 6, v188
	s_waitcnt lgkmcnt(0)
	v_mfma_f32_32x32x16_bf16 v[66:81], v[118:121], v[102:105], v[66:81]
	ds_read_b128 v[102:105], v190 offset:128
	ds_read_b128 v[106:109], v190 offset:160
	s_waitcnt lgkmcnt(1)
	v_mfma_f32_32x32x16_bf16 v[66:81], v[102:105], v[98:101], v[66:81]
	s_waitcnt lgkmcnt(0)
	v_mfma_f32_32x32x16_bf16 v[66:81], v[106:109], v[94:97], v[66:81]
	ds_read_b128 v[94:97], v190 offset:192
	ds_read_b128 v[98:101], v190 offset:224
	s_waitcnt lgkmcnt(1)
	v_mfma_f32_32x32x16_bf16 v[66:81], v[94:97], v[90:93], v[66:81]
	s_waitcnt lgkmcnt(0)
	v_mfma_f32_32x32x16_bf16 v[66:81], v[98:101], v[86:89], v[66:81]
	ds_read_b128 v[86:89], v190 offset:256
	ds_read_b128 v[90:93], v190 offset:288
	s_waitcnt lgkmcnt(1)
	v_mfma_f32_32x32x16_bf16 v[66:81], v[86:89], v[122:125], v[66:81]
	s_waitcnt lgkmcnt(0)
	v_mfma_f32_32x32x16_bf16 v[66:81], v[90:93], v[114:117], v[66:81]
	ds_read_b128 v[90:93], v190 offset:320
	ds_read_b128 v[86:89], v190 offset:352
	s_waitcnt lgkmcnt(1)
	v_mfma_f32_32x32x16_bf16 v[66:81], v[90:93], v[126:129], v[66:81]
	ds_read2_b64 v[90:93], v234 offset1:2
	ds_read2_b64 v[94:97], v234 offset0:4 offset1:6
	ds_read2_b64 v[98:101], v233 offset0:32 offset1:34
	s_waitcnt lgkmcnt(3)
	v_mfma_f32_32x32x16_bf16 v[66:81], v[86:89], v[82:85], v[66:81]
	ds_read2_b64 v[84:87], v233 offset0:36 offset1:38
	ds_read2_b64 v[102:105], v231 offset0:64 offset1:66
	s_nop 9
	v_max_f32_e32 v0, v67, v67
	v_max_f32_e32 v82, v66, v66
	v_max_f32_e32 v0, v82, v0
	v_max3_f32 v0, v0, v68, v69
	v_max3_f32 v0, v0, v70, v71
	v_max3_f32 v0, v0, v72, v73
	v_max3_f32 v0, v0, v74, v75
	v_max3_f32 v0, v0, v76, v77
	v_max3_f32 v0, v0, v78, v79
	v_max3_f32 v0, v0, v80, v81
	v_mov_b32_e32 v83, v0
	v_mov_b32_e32 v88, v81
	v_and_b32_e32 v82, 1, v110
	v_permlane32_swap_b32 v83, v0
	s_waitcnt lgkmcnt(0)
	v_max3_f32 v89, v185, v0, v83
	v_sub_f32_e32 v0, v185, v89
	v_pk_mul_f32 v[106:107], v[88:89], s[26:27] op_sel_hi:[1,0]
	v_mul_f32_e32 v0, 0x3dd53b94, v0
	v_fma_f32 v66, v66, s26, -v107
	v_fma_f32 v67, v67, s26, -v107
	v_fma_f32 v68, v68, s26, -v107
	v_fma_f32 v69, v69, s26, -v107
	v_fma_f32 v70, v70, s26, -v107
	v_fma_f32 v71, v71, s26, -v107
	v_fma_f32 v72, v72, s26, -v107
	v_fma_f32 v73, v73, s26, -v107
	v_exp_f32_e32 v0, v0
	v_exp_f32_e32 v88, v66
	v_exp_f32_e32 v111, v67
	v_exp_f32_e32 v112, v68
	v_exp_f32_e32 v113, v69
	v_exp_f32_e32 v114, v70
	v_exp_f32_e32 v115, v71
	v_exp_f32_e32 v116, v72
	v_exp_f32_e32 v117, v73
	v_fma_f32 v74, v74, s26, -v107
	v_fma_f32 v75, v75, s26, -v107
	v_fma_f32 v76, v76, s26, -v107
	v_fma_f32 v77, v77, s26, -v107
	v_fma_f32 v78, v78, s26, -v107
	v_fma_f32 v79, v79, s26, -v107
	v_fma_f32 v80, v80, s26, -v107
	v_sub_f32_e32 v83, v106, v107
	v_exp_f32_e32 v118, v74
	v_exp_f32_e32 v119, v75
	v_exp_f32_e32 v120, v76
	v_exp_f32_e32 v121, v77
	v_exp_f32_e32 v122, v78
	v_exp_f32_e32 v123, v79
	v_exp_f32_e32 v124, v80
	v_pk_mul_f32 v[80:81], v[16:17], v[0:1] op_sel_hi:[1,0]
	v_pk_mul_f32 v[78:79], v[14:15], v[0:1] op_sel_hi:[1,0]
	v_pk_mul_f32 v[76:77], v[12:13], v[0:1] op_sel_hi:[1,0]
	v_pk_mul_f32 v[74:75], v[10:11], v[0:1] op_sel_hi:[1,0]
	v_pk_mul_f32 v[72:73], v[8:9], v[0:1] op_sel_hi:[1,0]
	v_pk_mul_f32 v[70:71], v[6:7], v[0:1] op_sel_hi:[1,0]
	v_pk_mul_f32 v[68:69], v[4:5], v[0:1] op_sel_hi:[1,0]
	v_pk_mul_f32 v[66:67], v[2:3], v[0:1] op_sel_hi:[1,0]
	v_pk_mul_f32 v[16:17], v[48:49], v[0:1] op_sel_hi:[1,0]
	v_cvt_pk_bf16_f32 v106, v88, v111
	v_cvt_pk_bf16_f32 v107, v112, v113
	v_cvt_pk_bf16_f32 v108, v114, v115
	v_cvt_pk_bf16_f32 v109, v116, v117
	v_pk_mul_f32 v[14:15], v[46:47], v[0:1] op_sel_hi:[1,0]
	v_pk_mul_f32 v[12:13], v[44:45], v[0:1] op_sel_hi:[1,0]
	v_pk_mul_f32 v[10:11], v[42:43], v[0:1] op_sel_hi:[1,0]
	v_pk_mul_f32 v[8:9], v[40:41], v[0:1] op_sel_hi:[1,0]
	v_pk_mul_f32 v[6:7], v[38:39], v[0:1] op_sel_hi:[1,0]
	v_pk_mul_f32 v[4:5], v[36:37], v[0:1] op_sel_hi:[1,0]
	v_pk_mul_f32 v[2:3], v[34:35], v[0:1] op_sel_hi:[1,0]
	v_pk_mul_f32 v[48:49], v[64:65], v[0:1] op_sel_hi:[1,0]
	v_pk_mul_f32 v[46:47], v[62:63], v[0:1] op_sel_hi:[1,0]
	v_pk_mul_f32 v[44:45], v[60:61], v[0:1] op_sel_hi:[1,0]
	v_pk_mul_f32 v[42:43], v[58:59], v[0:1] op_sel_hi:[1,0]
	v_pk_mul_f32 v[40:41], v[56:57], v[0:1] op_sel_hi:[1,0]
	v_pk_mul_f32 v[38:39], v[54:55], v[0:1] op_sel_hi:[1,0]
	v_pk_mul_f32 v[36:37], v[52:53], v[0:1] op_sel_hi:[1,0]
	v_pk_mul_f32 v[34:35], v[50:51], v[0:1] op_sel_hi:[1,0]
	ds_read2_b64 v[50:53], v231 offset0:68 offset1:70
	v_add_f32_e32 v54, 0, v88
	v_mfma_f32_32x32x16_bf16 v[34:49], v[102:105], v[106:109], v[34:49]
	v_add_f32_e32 v54, v111, v54
	v_exp_f32_e32 v83, v83
	v_add_f32_e32 v54, v112, v54
	v_add_f32_e32 v54, v113, v54
	v_add_f32_e32 v58, v114, v54
	ds_read2_b64 v[54:57], v232 offset0:96 offset1:98
	v_cvt_pk_bf16_f32 v62, v118, v119
	v_cvt_pk_bf16_f32 v63, v120, v121
	v_cvt_pk_bf16_f32 v64, v122, v123
	v_cvt_pk_bf16_f32 v65, v124, v83
	v_mfma_f32_32x32x16_bf16 v[66:81], v[90:93], v[106:109], v[66:81]
	v_mul_f32_e64 v32, v32, v0
	v_mul_f32_e64 v33, v33, v0
	v_mul_f32_e64 v30, v30, v0
	v_mul_f32_e64 v31, v31, v0
	v_mul_f32_e64 v28, v28, v0
	v_mul_f32_e64 v29, v29, v0
	v_pk_mul_f32 v[26:27], v[26:27], v[0:1] op_sel_hi:[1,0]
	v_pk_mul_f32 v[24:25], v[24:25], v[0:1] op_sel_hi:[1,0]
	v_pk_mul_f32 v[22:23], v[22:23], v[0:1] op_sel_hi:[1,0]
	v_pk_mul_f32 v[20:21], v[20:21], v[0:1] op_sel_hi:[1,0]
	s_waitcnt lgkmcnt(1)
	v_mfma_f32_32x32x16_bf16 v[34:49], v[50:53], v[62:65], v[34:49]
	v_add_f32_e32 v50, v115, v58
	v_add_f32_e32 v50, v116, v50
	v_add_f32_e32 v50, v117, v50
	v_add_f32_e32 v50, v118, v50
	v_add_f32_e32 v50, v119, v50
	v_pk_mul_f32 v[18:19], v[18:19], v[0:1] op_sel_hi:[1,0]
	v_add_f32_e32 v58, v120, v50
	ds_read2_b64 v[50:53], v232 offset0:100 offset1:102
	s_waitcnt lgkmcnt(1)
	v_mfma_f32_32x32x16_bf16 v[18:33], v[54:57], v[106:109], v[18:33]
	v_add_f32_e32 v54, v121, v58
	v_add_f32_e32 v54, v122, v54
	v_add_f32_e32 v54, v123, v54
	v_add_f32_e32 v54, v124, v54
	v_add_f32_e32 v54, v83, v54
	v_fmac_f32_e32 v54, v184, v0
	v_mov_b32_e32 v0, v54
	v_mfma_f32_32x32x16_bf16 v[2:17], v[98:101], v[106:109], v[2:17]
	s_nop 1
	v_permlane32_swap_b32 v0, v54
	s_waitcnt lgkmcnt(0)
	s_barrier
	v_add_f32_e32 v0, v54, v0
	v_mfma_f32_32x32x16_bf16 v[66:81], v[94:97], v[62:65], v[66:81]
	v_mfma_f32_32x32x16_bf16 v[18:33], v[50:53], v[62:65], v[18:33]
	v_lshlrev_b32_e32 v50, 9, v110
	v_lshlrev_b32_e32 v51, 2, v186
	v_add3_u32 v50, s4, v50, v51
	ds_write2st64_b32 v50, v89, v0 offset1:1
	v_lshlrev_b32_e32 v0, 14, v110
	v_add3_u32 v0, 0, v0, v51
	v_mfma_f32_32x32x16_bf16 v[2:17], v[84:87], v[62:65], v[2:17]
	s_nop 3
	ds_write2st64_b32 v0, v66, v67 offset1:1
	ds_write2st64_b32 v0, v68, v69 offset0:2 offset1:3
	ds_write2st64_b32 v0, v70, v71 offset0:4 offset1:5
	ds_write2st64_b32 v0, v72, v73 offset0:6 offset1:7
	ds_write2st64_b32 v0, v74, v75 offset0:8 offset1:9
	ds_write2st64_b32 v0, v76, v77 offset0:10 offset1:11
	ds_write2st64_b32 v0, v78, v79 offset0:12 offset1:13
	ds_write2st64_b32 v0, v80, v81 offset0:14 offset1:15
	ds_write2st64_b32 v0, v2, v3 offset0:16 offset1:17
	ds_write2st64_b32 v0, v4, v5 offset0:18 offset1:19
	ds_write2st64_b32 v0, v6, v7 offset0:20 offset1:21
	ds_write2st64_b32 v0, v8, v9 offset0:22 offset1:23
	ds_write2st64_b32 v0, v10, v11 offset0:24 offset1:25
	ds_write2st64_b32 v0, v12, v13 offset0:26 offset1:27
	ds_write2st64_b32 v0, v14, v15 offset0:28 offset1:29
	ds_write2st64_b32 v0, v16, v17 offset0:30 offset1:31
	ds_write2st64_b32 v0, v34, v35 offset0:32 offset1:33
	ds_write2st64_b32 v0, v36, v37 offset0:34 offset1:35
	ds_write2st64_b32 v0, v38, v39 offset0:36 offset1:37
	ds_write2st64_b32 v0, v40, v41 offset0:38 offset1:39
	ds_write2st64_b32 v0, v42, v43 offset0:40 offset1:41
	ds_write2st64_b32 v0, v44, v45 offset0:42 offset1:43
	ds_write2st64_b32 v0, v46, v47 offset0:44 offset1:45
	ds_write2st64_b32 v0, v48, v49 offset0:46 offset1:47
	ds_write2st64_b32 v0, v18, v19 offset0:48 offset1:49
	ds_write2st64_b32 v0, v20, v21 offset0:50 offset1:51
	ds_write2st64_b32 v0, v22, v23 offset0:52 offset1:53
	ds_write2st64_b32 v0, v24, v25 offset0:54 offset1:55
	ds_write2st64_b32 v0, v26, v27 offset0:56 offset1:57
	ds_write2st64_b32 v0, v28, v29 offset0:58 offset1:59
	ds_write2st64_b32 v0, v30, v31 offset0:60 offset1:61
	ds_write2st64_b32 v0, v32, v33 offset0:62 offset1:63
	v_lshlrev_b32_e32 v0, 9, v82
	v_add3_u32 v0, s4, v0, v51
	s_waitcnt lgkmcnt(0)
	s_barrier
	ds_read2st64_b32 v[4:5], v0 offset1:1
	ds_read2st64_b32 v[6:7], v0 offset0:4 offset1:5
	ds_read2st64_b32 v[8:9], v0 offset0:8 offset1:9
	ds_read2st64_b32 v[10:11], v0 offset0:12 offset1:13
	s_lshl_b64 s[4:5], s[38:39], 11
	s_waitcnt lgkmcnt(2)
	v_max3_f32 v0, v4, s7, v6
	s_add_u32 s7, s80, s4
	s_waitcnt lgkmcnt(0)
	v_max3_f32 v0, v0, v8, v10
	v_sub_f32_e32 v2, v4, v0
	v_mul_f32_e32 v2, 0x3dd53b94, v2
	v_exp_f32_e32 v3, v2
	v_sub_f32_e32 v2, v6, v0
	v_mul_f32_e32 v2, 0x3dd53b94, v2
	v_exp_f32_e32 v2, v2
	v_mov_b32_e32 v4, v7
	s_addc_u32 s10, s81, s5
	v_pk_mul_f32 v[6:7], v[4:5], v[2:3]
	v_sub_f32_e32 v4, v8, v0
	v_sub_f32_e32 v0, v10, v0
	v_mul_f32_e32 v4, 0x3dd53b94, v4
	v_mul_f32_e32 v0, 0x3dd53b94, v0
	v_exp_f32_e32 v5, v4
	v_exp_f32_e32 v4, v0
	v_add_f32_e32 v0, 0, v7
	v_mov_b32_e32 v8, v11
	v_add_f32_e32 v0, v6, v0
	v_pk_mul_f32 v[6:7], v[8:9], v[4:5]
	s_nop 0
	v_add_f32_e32 v0, v7, v0
	v_add_f32_e32 v0, v6, v0
	v_div_scale_f32 v6, s[4:5], v0, v0, 1.0
	v_rcp_f32_e32 v7, v6
	s_lshl_b32 s4, s14, 1
	s_add_u32 s38, s7, s4
	s_addc_u32 s39, s10, 0
	v_fma_f32 v8, -v6, v7, 1.0
	v_fmac_f32_e32 v7, v8, v7
	v_div_scale_f32 v8, vcc, 1.0, v0, 1.0
	v_mul_f32_e32 v9, v8, v7
	v_fma_f32 v10, -v6, v9, v8
	v_fmac_f32_e32 v9, v10, v7
	v_fma_f32 v6, -v6, v9, v8
	v_div_fmas_f32 v6, v6, v7, v9
	v_div_fixup_f32 v0, v6, v0, 1.0
	v_lshl_add_u32 v6, v82, 14, 0
	v_lshlrev_b32_e32 v7, 12, v177
	v_add3_u32 v7, v6, v7, v51
	ds_read2st64_b32 v[8:9], v7 offset1:1
	ds_read2st64_b32 v[10:11], v7 offset0:128 offset1:129
	v_mov_b32_e32 v6, v3
	v_add_u32_e32 v24, 0x10000, v7
	v_add_u32_e32 v25, 0x18000, v7
	v_add_u32_e32 v27, 0x10100, v7
	v_add_u32_e32 v28, 0x18100, v7
	ds_read2st64_b32 v[12:13], v7 offset0:2 offset1:3
	ds_read2st64_b32 v[14:15], v7 offset0:4 offset1:5
	ds_read2st64_b32 v[16:17], v7 offset0:6 offset1:7
	s_waitcnt lgkmcnt(4)
	v_pk_fma_f32 v[8:9], v[8:9], v[6:7], 0 op_sel_hi:[1,0,0]
	v_add_u32_e32 v31, 0x18300, v7
	ds_read2st64_b32 v[18:19], v7 offset0:130 offset1:131
	ds_read2st64_b32 v[20:21], v7 offset0:132 offset1:133
	ds_read2st64_b32 v[22:23], v7 offset0:134 offset1:135
	s_waitcnt lgkmcnt(6)
	v_pk_fma_f32 v[8:9], v[10:11], v[2:3], v[8:9] op_sel_hi:[1,0,1]
	v_mov_b32_e32 v10, v5
	v_add_u32_e32 v3, 0x10200, v7
	v_add_u32_e32 v5, 0x18200, v7
	v_add_u32_e32 v11, 0x10300, v7
	ds_read_b32 v24, v24
	ds_read_b32 v26, v25
	ds_read_b32 v25, v27
	ds_read_b32 v27, v28
	ds_read_b32 v28, v3
	ds_read_b32 v30, v5
	ds_read_b32 v29, v11
	ds_read_b32 v31, v31
	s_waitcnt lgkmcnt(13)
	v_pk_fma_f32 v[12:13], v[6:7], v[12:13], 0 op_sel_hi:[0,1,0]
	s_waitcnt lgkmcnt(5)
	v_pk_fma_f32 v[8:9], v[10:11], v[24:25], v[8:9] op_sel_hi:[0,1,1]
	v_pk_fma_f32 v[12:13], v[2:3], v[18:19], v[12:13] op_sel_hi:[0,1,1]
	v_add_u32_e32 v3, 0x10400, v7
	v_pk_fma_f32 v[14:15], v[6:7], v[14:15], 0 op_sel_hi:[0,1,0]
	s_waitcnt lgkmcnt(4)
	v_pk_fma_f32 v[8:9], v[4:5], v[26:27], v[8:9] op_sel_hi:[0,1,1]
	s_waitcnt lgkmcnt(1)
	v_pk_fma_f32 v[12:13], v[10:11], v[28:29], v[12:13] op_sel_hi:[0,1,1]
	v_add_u32_e32 v11, 0x10500, v7
	v_add_u32_e32 v24, 0x18500, v7
	v_pk_fma_f32 v[14:15], v[2:3], v[20:21], v[14:15] op_sel_hi:[0,1,1]
	v_add_u32_e32 v25, 0x10600, v7
	v_add_u32_e32 v26, 0x18600, v7
	v_add_u32_e32 v27, 0x10700, v7
	s_waitcnt lgkmcnt(0)
	v_pk_fma_f32 v[12:13], v[4:5], v[30:31], v[12:13] op_sel_hi:[0,1,1]
	v_add_u32_e32 v5, 0x18400, v7
	v_add_u32_e32 v28, 0x18700, v7
	ds_read_b32 v18, v3
	ds_read_b32 v20, v5
	ds_read_b32 v19, v11
	ds_read_b32 v21, v24
	ds_read_b32 v24, v25
	ds_read_b32 v26, v26
	ds_read_b32 v25, v27
	ds_read_b32 v27, v28
	s_waitcnt lgkmcnt(5)
	v_pk_fma_f32 v[14:15], v[10:11], v[18:19], v[14:15] op_sel_hi:[0,1,1]
	s_waitcnt lgkmcnt(4)
	v_pk_fma_f32 v[14:15], v[4:5], v[20:21], v[14:15] op_sel_hi:[0,1,1]
	ds_read2st64_b32 v[18:19], v7 offset0:8 offset1:9
	ds_read2st64_b32 v[20:21], v7 offset0:136 offset1:137
	v_pk_fma_f32 v[16:17], v[6:7], v[16:17], 0 op_sel_hi:[0,1,0]
	v_pk_fma_f32 v[16:17], v[2:3], v[22:23], v[16:17] op_sel_hi:[0,1,1]
	s_waitcnt lgkmcnt(3)
	v_pk_fma_f32 v[16:17], v[10:11], v[24:25], v[16:17] op_sel_hi:[0,1,1]
	s_waitcnt lgkmcnt(2)
	v_pk_fma_f32 v[16:17], v[4:5], v[26:27], v[16:17] op_sel_hi:[0,1,1]
	v_add_u32_e32 v3, 0x10800, v7
	v_add_u32_e32 v35, 0x18900, v7
	ds_read2st64_b32 v[22:23], v7 offset0:10 offset1:11
	ds_read2st64_b32 v[24:25], v7 offset0:12 offset1:13
	ds_read2st64_b32 v[26:27], v7 offset0:14 offset1:15
	s_waitcnt lgkmcnt(4)
	v_pk_fma_f32 v[18:19], v[6:7], v[18:19], 0 op_sel_hi:[0,1,0]
	v_add_u32_e32 v36, 0x10a00, v7
	v_add_u32_e32 v37, 0x18a00, v7
	v_add_u32_e32 v39, 0x10b00, v7
	v_add_u32_e32 v5, 0x18800, v7
	v_add_u32_e32 v11, 0x10900, v7
	ds_read2st64_b32 v[28:29], v7 offset0:138 offset1:139
	ds_read2st64_b32 v[30:31], v7 offset0:140 offset1:141
	ds_read2st64_b32 v[32:33], v7 offset0:142 offset1:143
	s_waitcnt lgkmcnt(6)
	v_pk_fma_f32 v[18:19], v[2:3], v[20:21], v[18:19] op_sel_hi:[0,1,1]
	v_add_u32_e32 v40, 0x18b00, v7
	ds_read_b32 v20, v3
	ds_read_b32 v34, v5
	ds_read_b32 v21, v11
	ds_read_b32 v35, v35
	ds_read_b32 v36, v36
	ds_read_b32 v38, v37
	ds_read_b32 v37, v39
	ds_read_b32 v39, v40
	s_waitcnt lgkmcnt(5)
	v_pk_fma_f32 v[18:19], v[10:11], v[20:21], v[18:19] op_sel_hi:[0,1,1]
	v_pk_fma_f32 v[20:21], v[6:7], v[22:23], 0 op_sel_hi:[0,1,0]
	v_pk_fma_f32 v[20:21], v[2:3], v[28:29], v[20:21] op_sel_hi:[0,1,1]
	v_add_u32_e32 v3, 0x10c00, v7
	v_pk_fma_f32 v[22:23], v[6:7], v[24:25], 0 op_sel_hi:[0,1,0]
	s_waitcnt lgkmcnt(4)
	v_pk_fma_f32 v[18:19], v[4:5], v[34:35], v[18:19] op_sel_hi:[0,1,1]
	s_waitcnt lgkmcnt(1)
	v_pk_fma_f32 v[20:21], v[10:11], v[36:37], v[20:21] op_sel_hi:[0,1,1]
	v_add_u32_e32 v29, 0x18d00, v7
	v_pk_fma_f32 v[22:23], v[2:3], v[30:31], v[22:23] op_sel_hi:[0,1,1]
	v_add_u32_e32 v30, 0x10e00, v7
	v_add_u32_e32 v31, 0x18e00, v7
	v_add_u32_e32 v35, 0x10f00, v7
	s_waitcnt lgkmcnt(0)
	v_pk_fma_f32 v[20:21], v[4:5], v[38:39], v[20:21] op_sel_hi:[0,1,1]
	v_add_u32_e32 v5, 0x18c00, v7
	v_add_u32_e32 v11, 0x10d00, v7
	v_add_u32_e32 v7, 0x18f00, v7
	ds_read_b32 v24, v3
	ds_read_b32 v28, v5
	ds_read_b32 v25, v11
	ds_read_b32 v29, v29
	ds_read_b32 v30, v30
	ds_read_b32 v34, v31
	ds_read_b32 v31, v35
	ds_read_b32 v35, v7
	v_pk_fma_f32 v[6:7], v[6:7], v[26:27], 0 op_sel_hi:[0,1,0]
	v_pk_fma_f32 v[2:3], v[2:3], v[32:33], v[6:7] op_sel_hi:[0,1,1]
	s_waitcnt lgkmcnt(5)
	v_pk_fma_f32 v[22:23], v[10:11], v[24:25], v[22:23] op_sel_hi:[0,1,1]
	s_waitcnt lgkmcnt(1)
	v_pk_fma_f32 v[2:3], v[10:11], v[30:31], v[2:3] op_sel_hi:[0,1,1]
	v_pk_fma_f32 v[22:23], v[4:5], v[28:29], v[22:23] op_sel_hi:[0,1,1]
	s_waitcnt lgkmcnt(0)
	v_pk_fma_f32 v[2:3], v[4:5], v[34:35], v[2:3] op_sel_hi:[0,1,1]
	v_pk_mul_f32 v[8:9], v[8:9], v[0:1] op_sel_hi:[1,0]
	v_pk_mul_f32 v[12:13], v[0:1], v[12:13] op_sel_hi:[0,1]
	v_pk_mul_f32 v[14:15], v[0:1], v[14:15] op_sel_hi:[0,1]
	v_pk_mul_f32 v[16:17], v[0:1], v[16:17] op_sel_hi:[0,1]
	v_pk_mul_f32 v[18:19], v[0:1], v[18:19] op_sel_hi:[0,1]
	v_pk_mul_f32 v[20:21], v[0:1], v[20:21] op_sel_hi:[0,1]
	v_pk_mul_f32 v[22:23], v[0:1], v[22:23] op_sel_hi:[0,1]
	v_pk_mul_f32 v[2:3], v[0:1], v[2:3] op_sel_hi:[0,1]
	v_lshlrev_b32_e32 v0, 11, v175
	v_lshl_or_b32 v0, v82, 16, v0
	v_lshlrev_b32_e32 v6, 5, v177
	v_lshl_add_u64 v[4:5], s[38:39], 0, v[0:1]
	v_ashrrev_i32_e32 v7, 31, v6
	v_lshl_add_u64 v[4:5], v[6:7], 1, v[4:5]
	v_mov_b32_e32 v177, v1
	v_lshl_add_u64 v[4:5], v[4:5], 0, v[176:177]
	s_mov_b64 s[4:5], 0x4328400
	v_lshl_add_u64 v[6:7], v[4:5], 0, s[4:5]
	s_mov_b32 s4, 0x4328000
	v_add_co_u32_e32 v4, vcc, s4, v4
	v_cvt_pk_bf16_f32 v8, v8, v9
	v_cvt_pk_bf16_f32 v9, v12, v13
	v_addc_co_u32_e32 v5, vcc, 0, v5, vcc
	global_store_dwordx2 v[4:5], v[8:9], off offset:1024
	v_cvt_pk_bf16_f32 v4, v14, v15
	v_cvt_pk_bf16_f32 v5, v16, v17
	global_store_dwordx2 v[6:7], v[4:5], off offset:16
	v_cvt_pk_bf16_f32 v4, v18, v19
	v_cvt_pk_bf16_f32 v5, v20, v21
	global_store_dwordx2 v[6:7], v[4:5], off offset:32
	v_cvt_pk_bf16_f32 v4, v22, v23
	v_cvt_pk_bf16_f32 v5, v2, v3
	global_store_dwordx2 v[6:7], v[4:5], off offset:48
	s_barrier
	s_mov_b64 s[14:15], 0
